# th1 plus SwiGLU epilogue scalar f32 mul/add pairs packed into v_pk_mul_f32/v_pk_add_f32 (52 fewer VALU per wave per unit, bit-identical)
# speedup vs baseline: 1.0077x; 1.0077x over previous
.LBB0_263:
	s_waitcnt lgkmcnt(0)
	v_mul_f32_e32 v152, 0xbfb8aa3b, v174
	v_mul_f32_e32 v148, v144, v152
	v_exp_f32_e32 v150, v148
	v_mul_f32_e32 v148, v145, v152
	v_exp_f32_e32 v151, v148
	v_mul_f32_e32 v153, v146, v152
	v_mul_f32_e32 v154, v147, v152
	v_exp_f32_e32 v153, v153
	v_exp_f32_e32 v154, v154
	v_pk_add_f32 v[150:151], v[150:151], 1.0 op_sel_hi:[1,0]
	v_rcp_f32_e32 v150, v150
	v_rcp_f32_e32 v151, v151
	v_pk_mul_f32 v[142:143], v[146:147], v[142:143]
	v_add_f32_e32 v146, 1.0, v153
	v_add_f32_e32 v147, 1.0, v154
	v_rcp_f32_e32 v146, v146
	v_rcp_f32_e32 v147, v147
	v_lshl_or_b32 v149, s47, 7, v193
	v_lshrrev_b32_e32 v246, 4, v172
	v_mul_u32_u24_e32 v246, 0xb0, v246
	v_lshrrev_b32_e32 v247, 5, v149
	v_add_lshl_u32 v246, v246, v247, 10
	v_and_b32_e32 v247, 15, v172
	v_lshl_or_b32 v246, v247, 6, v246
	v_lshrrev_b32_e32 v247, 2, v172
	v_and_b32_e32 v247, 2, v247
	v_bfe_u32 v248, v149, 3, 2
	v_xor_b32_e32 v247, v248, v247
	v_lshl_or_b32 v246, v247, 4, v246
	v_mul_f32_e32 v148, v174, v174
	v_pk_mul_f32 v[140:141], v[144:145], v[140:141]
	v_pk_mul_f32 v[144:145], v[148:149], v[150:151] op_sel_hi:[0,1]
	v_pk_mul_f32 v[140:141], v[140:141], v[144:145]
	v_pk_mul_f32 v[144:145], v[148:149], v[146:147] op_sel_hi:[0,1]
	v_pk_mul_f32 v[146:147], v[136:137], v[152:153] op_sel_hi:[1,0]
	v_exp_f32_e32 v146, v146
	v_exp_f32_e32 v147, v147
	v_pk_mul_f32 v[142:143], v[142:143], v[144:145]
	v_pk_mul_f32 v[134:135], v[138:139], v[134:135]
	v_pk_add_f32 v[144:145], v[146:147], 1.0 op_sel_hi:[1,0]
	v_pk_mul_f32 v[146:147], v[138:139], v[152:153] op_sel_hi:[1,0]
	v_exp_f32_e32 v146, v146
	v_exp_f32_e32 v147, v147
	v_rcp_f32_e32 v144, v144
	v_rcp_f32_e32 v145, v145
	v_pk_add_f32 v[138:139], v[146:147], 1.0 op_sel_hi:[1,0]
	v_rcp_f32_e32 v138, v138
	v_rcp_f32_e32 v139, v139
	v_pk_mul_f32 v[132:133], v[136:137], v[132:133]
	v_pk_mul_f32 v[136:137], v[148:149], v[144:145] op_sel_hi:[0,1]
	v_pk_mul_f32 v[136:137], v[132:133], v[136:137]
	v_pk_mul_f32 v[132:133], v[148:149], v[138:139] op_sel_hi:[0,1]
	s_movk_i32 s6, 0x1600
	v_pk_mul_f32 v[138:139], v[134:135], v[132:133]
	v_cvt_pk_bf16_f32 v134, v136, v137
	v_nop
	v_readlane_b32 s2, v252, 55
	v_cvt_pk_bf16_f32 v132, v140, v141
	v_cvt_pk_bf16_f32 v133, v142, v143
	v_cvt_pk_bf16_f32 v135, v138, v139
	v_nop
	v_readlane_b32 s3, v252, 56
	v_pk_mul_f32 v[126:127], v[130:131], v[126:127]
	v_pk_mul_f32 v[124:125], v[128:129], v[124:125]
	v_pk_mul_f32 v[118:119], v[122:123], v[118:119]
	v_pk_mul_f32 v[116:117], v[120:121], v[116:117]
	v_pk_mul_f32 v[110:111], v[114:115], v[110:111]
	global_store_dwordx4 v246, v[132:135], s[2:3]
	v_pk_mul_f32 v[108:109], v[112:113], v[108:109]
	v_pk_mul_f32 v[102:103], v[106:107], v[102:103]
	v_mul_f32_e32 v133, 0xbfb8aa3b, v175
	v_mul_f32_e32 v132, v128, v133
	v_exp_f32_e32 v134, v132
	v_mul_f32_e32 v132, v129, v133
	v_exp_f32_e32 v135, v132
	v_pk_mul_f32 v[136:137], v[130:131], v[132:133] op_sel:[0,1]
	v_exp_f32_e32 v136, v136
	v_exp_f32_e32 v137, v137
	v_pk_add_f32 v[134:135], v[134:135], 1.0 op_sel_hi:[1,0]
	v_rcp_f32_e32 v134, v134
	v_rcp_f32_e32 v135, v135
	v_pk_add_f32 v[130:131], v[136:137], 1.0 op_sel_hi:[1,0]
	v_rcp_f32_e32 v130, v130
	v_rcp_f32_e32 v131, v131
	v_mul_f32_e32 v132, v175, v175
	v_pk_mul_f32 v[128:129], v[132:133], v[134:135] op_sel_hi:[0,1]
	v_pk_mul_f32 v[124:125], v[124:125], v[128:129]
	v_pk_mul_f32 v[128:129], v[132:133], v[130:131] op_sel_hi:[0,1]
	v_pk_mul_f32 v[130:131], v[120:121], v[132:133] op_sel:[0,1]
	v_exp_f32_e32 v130, v130
	v_exp_f32_e32 v131, v131
	v_pk_mul_f32 v[126:127], v[126:127], v[128:129]
	v_pk_mul_f32 v[100:101], v[104:105], v[100:101]
	v_pk_add_f32 v[128:129], v[130:131], 1.0 op_sel_hi:[1,0]
	v_pk_mul_f32 v[130:131], v[122:123], v[132:133] op_sel:[0,1]
	v_exp_f32_e32 v130, v130
	v_exp_f32_e32 v131, v131
	v_rcp_f32_e32 v128, v128
	v_rcp_f32_e32 v129, v129
	v_pk_add_f32 v[122:123], v[130:131], 1.0 op_sel_hi:[1,0]
	v_rcp_f32_e32 v122, v122
	v_rcp_f32_e32 v123, v123
	v_pk_mul_f32 v[120:121], v[132:133], v[128:129] op_sel_hi:[0,1]
	v_pk_mul_f32 v[120:121], v[116:117], v[120:121]
	v_pk_mul_f32 v[94:95], v[98:99], v[94:95]
	v_pk_mul_f32 v[116:117], v[132:133], v[122:123] op_sel_hi:[0,1]
	v_pk_mul_f32 v[122:123], v[118:119], v[116:117]
	v_cvt_pk_bf16_f32 v118, v120, v121
	v_nop
	v_cvt_pk_bf16_f32 v116, v124, v125
	v_cvt_pk_bf16_f32 v117, v126, v127
	v_cvt_pk_bf16_f32 v119, v122, v123
	v_nop
	v_add_u32_e32 v247, 0x2c000, v246
	global_store_dwordx4 v247, v[116:119], s[2:3]
	v_pk_mul_f32 v[92:93], v[96:97], v[92:93]
	v_pk_mul_f32 v[86:87], v[90:91], v[86:87]
	v_mul_f32_e32 v117, 0xbfb8aa3b, v176
	v_mul_f32_e32 v116, v112, v117
	v_exp_f32_e32 v118, v116
	v_mul_f32_e32 v116, v113, v117
	v_exp_f32_e32 v119, v116
	v_pk_mul_f32 v[120:121], v[114:115], v[116:117] op_sel:[0,1]
	v_exp_f32_e32 v120, v120
	v_exp_f32_e32 v121, v121
	v_pk_add_f32 v[118:119], v[118:119], 1.0 op_sel_hi:[1,0]
	v_rcp_f32_e32 v118, v118
	v_rcp_f32_e32 v119, v119
	v_pk_add_f32 v[114:115], v[120:121], 1.0 op_sel_hi:[1,0]
	v_rcp_f32_e32 v114, v114
	v_rcp_f32_e32 v115, v115
	v_mul_f32_e32 v116, v176, v176
	v_pk_mul_f32 v[112:113], v[116:117], v[118:119] op_sel_hi:[0,1]
	v_pk_mul_f32 v[108:109], v[108:109], v[112:113]
	v_pk_mul_f32 v[112:113], v[116:117], v[114:115] op_sel_hi:[0,1]
	v_pk_mul_f32 v[114:115], v[104:105], v[116:117] op_sel:[0,1]
	v_exp_f32_e32 v114, v114
	v_exp_f32_e32 v115, v115
	v_pk_mul_f32 v[110:111], v[110:111], v[112:113]
	v_pk_mul_f32 v[84:85], v[88:89], v[84:85]
	v_pk_add_f32 v[112:113], v[114:115], 1.0 op_sel_hi:[1,0]
	v_pk_mul_f32 v[114:115], v[106:107], v[116:117] op_sel:[0,1]
	v_exp_f32_e32 v114, v114
	v_exp_f32_e32 v115, v115
	v_rcp_f32_e32 v112, v112
	v_rcp_f32_e32 v113, v113
	v_pk_add_f32 v[106:107], v[114:115], 1.0 op_sel_hi:[1,0]
	v_rcp_f32_e32 v106, v106
	v_rcp_f32_e32 v107, v107
	v_pk_mul_f32 v[104:105], v[116:117], v[112:113] op_sel_hi:[0,1]
	v_pk_mul_f32 v[104:105], v[100:101], v[104:105]
	v_pk_mul_f32 v[78:79], v[82:83], v[78:79]
	v_pk_mul_f32 v[100:101], v[116:117], v[106:107] op_sel_hi:[0,1]
	v_pk_mul_f32 v[106:107], v[102:103], v[100:101]
	v_cvt_pk_bf16_f32 v102, v104, v105
	v_nop
	v_cvt_pk_bf16_f32 v100, v108, v109
	v_cvt_pk_bf16_f32 v101, v110, v111
	v_cvt_pk_bf16_f32 v103, v106, v107
	v_nop
	v_add_u32_e32 v247, 0x58000, v246
	global_store_dwordx4 v247, v[100:103], s[2:3]
	v_pk_mul_f32 v[76:77], v[80:81], v[76:77]
	v_pk_mul_f32 v[70:71], v[74:75], v[70:71]
	v_mul_f32_e32 v101, 0xbfb8aa3b, v177
	v_mul_f32_e32 v100, v96, v101
	v_exp_f32_e32 v102, v100
	v_mul_f32_e32 v100, v97, v101
	v_exp_f32_e32 v103, v100
	v_pk_mul_f32 v[104:105], v[98:99], v[100:101] op_sel:[0,1]
	v_exp_f32_e32 v104, v104
	v_exp_f32_e32 v105, v105
	v_pk_add_f32 v[102:103], v[102:103], 1.0 op_sel_hi:[1,0]
	v_rcp_f32_e32 v102, v102
	v_rcp_f32_e32 v103, v103
	v_pk_add_f32 v[98:99], v[104:105], 1.0 op_sel_hi:[1,0]
	v_rcp_f32_e32 v98, v98
	v_rcp_f32_e32 v99, v99
	v_mul_f32_e32 v100, v177, v177
	v_pk_mul_f32 v[96:97], v[100:101], v[102:103] op_sel_hi:[0,1]
	v_pk_mul_f32 v[92:93], v[92:93], v[96:97]
	v_pk_mul_f32 v[96:97], v[100:101], v[98:99] op_sel_hi:[0,1]
	v_pk_mul_f32 v[98:99], v[88:89], v[100:101] op_sel:[0,1]
	v_exp_f32_e32 v98, v98
	v_exp_f32_e32 v99, v99
	v_pk_mul_f32 v[94:95], v[94:95], v[96:97]
	v_pk_mul_f32 v[68:69], v[72:73], v[68:69]
	v_pk_add_f32 v[96:97], v[98:99], 1.0 op_sel_hi:[1,0]
	v_pk_mul_f32 v[98:99], v[90:91], v[100:101] op_sel:[0,1]
	v_exp_f32_e32 v98, v98
	v_exp_f32_e32 v99, v99
	v_rcp_f32_e32 v96, v96
	v_rcp_f32_e32 v97, v97
	v_pk_add_f32 v[90:91], v[98:99], 1.0 op_sel_hi:[1,0]
	v_rcp_f32_e32 v90, v90
	v_rcp_f32_e32 v91, v91
	v_pk_mul_f32 v[88:89], v[100:101], v[96:97] op_sel_hi:[0,1]
	v_pk_mul_f32 v[88:89], v[84:85], v[88:89]
	v_pk_mul_f32 v[62:63], v[66:67], v[62:63]
	v_pk_mul_f32 v[84:85], v[100:101], v[90:91] op_sel_hi:[0,1]
	v_pk_mul_f32 v[90:91], v[86:87], v[84:85]
	v_cvt_pk_bf16_f32 v86, v88, v89
	v_nop
	v_cvt_pk_bf16_f32 v84, v92, v93
	v_cvt_pk_bf16_f32 v85, v94, v95
	v_cvt_pk_bf16_f32 v87, v90, v91
	v_nop
	v_add_u32_e32 v247, 0x84000, v246
	global_store_dwordx4 v247, v[84:87], s[2:3]
	v_pk_mul_f32 v[60:61], v[64:65], v[60:61]
	v_pk_mul_f32 v[54:55], v[58:59], v[54:55]
	v_mul_f32_e32 v85, 0xbfb8aa3b, v184
	v_mul_f32_e32 v84, v80, v85
	v_exp_f32_e32 v86, v84
	v_mul_f32_e32 v84, v81, v85
	v_exp_f32_e32 v87, v84
	v_pk_mul_f32 v[88:89], v[82:83], v[84:85] op_sel:[0,1]
	v_exp_f32_e32 v88, v88
	v_exp_f32_e32 v89, v89
	v_pk_add_f32 v[86:87], v[86:87], 1.0 op_sel_hi:[1,0]
	v_rcp_f32_e32 v86, v86
	v_rcp_f32_e32 v87, v87
	v_pk_add_f32 v[82:83], v[88:89], 1.0 op_sel_hi:[1,0]
	v_rcp_f32_e32 v82, v82
	v_rcp_f32_e32 v83, v83
	v_mul_f32_e32 v84, v184, v184
	v_pk_mul_f32 v[80:81], v[84:85], v[86:87] op_sel_hi:[0,1]
	v_pk_mul_f32 v[76:77], v[76:77], v[80:81]
	v_pk_mul_f32 v[80:81], v[84:85], v[82:83] op_sel_hi:[0,1]
	v_pk_mul_f32 v[82:83], v[72:73], v[84:85] op_sel:[0,1]
	v_exp_f32_e32 v82, v82
	v_exp_f32_e32 v83, v83
	v_pk_mul_f32 v[78:79], v[78:79], v[80:81]
	v_pk_mul_f32 v[52:53], v[56:57], v[52:53]
	v_pk_add_f32 v[80:81], v[82:83], 1.0 op_sel_hi:[1,0]
	v_pk_mul_f32 v[82:83], v[74:75], v[84:85] op_sel:[0,1]
	v_exp_f32_e32 v82, v82
	v_exp_f32_e32 v83, v83
	v_rcp_f32_e32 v80, v80
	v_rcp_f32_e32 v81, v81
	v_pk_add_f32 v[74:75], v[82:83], 1.0 op_sel_hi:[1,0]
	v_rcp_f32_e32 v74, v74
	v_rcp_f32_e32 v75, v75
	v_pk_mul_f32 v[72:73], v[84:85], v[80:81] op_sel_hi:[0,1]
	v_pk_mul_f32 v[72:73], v[68:69], v[72:73]
	v_pk_mul_f32 v[46:47], v[50:51], v[46:47]
	v_pk_mul_f32 v[68:69], v[84:85], v[74:75] op_sel_hi:[0,1]
	v_pk_mul_f32 v[74:75], v[70:71], v[68:69]
	v_cvt_pk_bf16_f32 v70, v72, v73
	v_nop
	v_cvt_pk_bf16_f32 v68, v76, v77
	v_cvt_pk_bf16_f32 v69, v78, v79
	v_cvt_pk_bf16_f32 v71, v74, v75
	v_nop
	v_add_u32_e32 v247, 0x160000, v246
	global_store_dwordx4 v247, v[68:71], s[2:3]
	v_pk_mul_f32 v[44:45], v[48:49], v[44:45]
	v_pk_mul_f32 v[38:39], v[42:43], v[38:39]
	v_mul_f32_e32 v69, 0xbfb8aa3b, v185
	v_mul_f32_e32 v68, v64, v69
	v_exp_f32_e32 v70, v68
	v_mul_f32_e32 v68, v65, v69
	v_exp_f32_e32 v71, v68
	v_mul_f32_e32 v73, v66, v69
	v_mul_f32_e32 v74, v67, v69
	v_exp_f32_e32 v73, v73
	v_exp_f32_e32 v74, v74
	v_pk_add_f32 v[70:71], v[70:71], 1.0 op_sel_hi:[1,0]
	v_rcp_f32_e32 v70, v70
	v_rcp_f32_e32 v71, v71
	v_add_f32_e32 v66, 1.0, v73
	v_add_f32_e32 v67, 1.0, v74
	v_rcp_f32_e32 v66, v66
	v_rcp_f32_e32 v67, v67
	v_mul_f32_e32 v68, v185, v185
	v_pk_mul_f32 v[64:65], v[68:69], v[70:71] op_sel_hi:[0,1]
	v_pk_mul_f32 v[60:61], v[60:61], v[64:65]
	v_pk_mul_f32 v[64:65], v[68:69], v[66:67] op_sel_hi:[0,1]
	v_pk_mul_f32 v[66:67], v[56:57], v[68:69] op_sel:[0,1]
	v_exp_f32_e32 v66, v66
	v_exp_f32_e32 v67, v67
	v_pk_mul_f32 v[62:63], v[62:63], v[64:65]
	v_pk_mul_f32 v[36:37], v[40:41], v[36:37]
	v_pk_add_f32 v[64:65], v[66:67], 1.0 op_sel_hi:[1,0]
	v_pk_mul_f32 v[66:67], v[58:59], v[68:69] op_sel:[0,1]
	v_exp_f32_e32 v66, v66
	v_exp_f32_e32 v67, v67
	v_rcp_f32_e32 v64, v64
	v_rcp_f32_e32 v65, v65
	v_pk_add_f32 v[58:59], v[66:67], 1.0 op_sel_hi:[1,0]
	v_rcp_f32_e32 v58, v58
	v_rcp_f32_e32 v59, v59
	v_pk_mul_f32 v[56:57], v[68:69], v[64:65] op_sel_hi:[0,1]
	v_pk_mul_f32 v[56:57], v[52:53], v[56:57]
	v_pk_mul_f32 v[30:31], v[34:35], v[30:31]
	v_pk_mul_f32 v[52:53], v[68:69], v[58:59] op_sel_hi:[0,1]
	v_pk_mul_f32 v[58:59], v[54:55], v[52:53]
	v_cvt_pk_bf16_f32 v52, v60, v61
	v_cvt_pk_bf16_f32 v53, v62, v63
	v_cvt_pk_bf16_f32 v54, v56, v57
	v_cvt_pk_bf16_f32 v55, v58, v59
	v_nop
	v_add_u32_e32 v247, 0x18c000, v246
	global_store_dwordx4 v247, v[52:55], s[2:3]
	v_pk_mul_f32 v[28:29], v[32:33], v[28:29]
	v_pk_mul_f32 v[22:23], v[26:27], v[22:23]
	v_mul_f32_e32 v53, 0xbfb8aa3b, v188
	v_mul_f32_e32 v52, v48, v53
	v_exp_f32_e32 v54, v52
	v_mul_f32_e32 v52, v49, v53
	v_exp_f32_e32 v55, v52
	v_pk_mul_f32 v[56:57], v[50:51], v[52:53] op_sel:[0,1]
	v_exp_f32_e32 v56, v56
	v_exp_f32_e32 v57, v57
	v_pk_add_f32 v[54:55], v[54:55], 1.0 op_sel_hi:[1,0]
	v_rcp_f32_e32 v54, v54
	v_rcp_f32_e32 v55, v55
	v_pk_add_f32 v[50:51], v[56:57], 1.0 op_sel_hi:[1,0]
	v_rcp_f32_e32 v50, v50
	v_rcp_f32_e32 v51, v51
	v_mul_f32_e32 v52, v188, v188
	v_pk_mul_f32 v[48:49], v[52:53], v[54:55] op_sel_hi:[0,1]
	v_pk_mul_f32 v[44:45], v[44:45], v[48:49]
	v_pk_mul_f32 v[48:49], v[52:53], v[50:51] op_sel_hi:[0,1]
	v_pk_mul_f32 v[50:51], v[40:41], v[52:53] op_sel:[0,1]
	v_exp_f32_e32 v50, v50
	v_exp_f32_e32 v51, v51
	v_pk_mul_f32 v[46:47], v[46:47], v[48:49]
	v_pk_mul_f32 v[20:21], v[24:25], v[20:21]
	v_pk_add_f32 v[48:49], v[50:51], 1.0 op_sel_hi:[1,0]
	v_pk_mul_f32 v[50:51], v[42:43], v[52:53] op_sel:[0,1]
	v_exp_f32_e32 v50, v50
	v_exp_f32_e32 v51, v51
	v_rcp_f32_e32 v48, v48
	v_rcp_f32_e32 v49, v49
	v_pk_add_f32 v[42:43], v[50:51], 1.0 op_sel_hi:[1,0]
	v_rcp_f32_e32 v42, v42
	v_rcp_f32_e32 v43, v43
	v_pk_mul_f32 v[40:41], v[52:53], v[48:49] op_sel_hi:[0,1]
	v_pk_mul_f32 v[40:41], v[36:37], v[40:41]
	s_andn2_b64 vcc, exec, s[36:37]
	v_pk_mul_f32 v[36:37], v[52:53], v[42:43] op_sel_hi:[0,1]
	v_pk_mul_f32 v[42:43], v[38:39], v[36:37]
	v_cvt_pk_bf16_f32 v36, v44, v45
	v_cvt_pk_bf16_f32 v37, v46, v47
	v_cvt_pk_bf16_f32 v38, v40, v41
	v_cvt_pk_bf16_f32 v39, v42, v43
	v_nop
	v_add_u32_e32 v247, 0x1b8000, v246
	global_store_dwordx4 v247, v[36:39], s[2:3]
	s_nop 1
	v_mul_f32_e32 v37, 0xbfb8aa3b, v189
	v_mul_f32_e32 v36, v32, v37
	v_exp_f32_e32 v38, v36
	v_mul_f32_e32 v36, v33, v37
	v_exp_f32_e32 v39, v36
	v_pk_mul_f32 v[40:41], v[34:35], v[36:37] op_sel:[0,1]
	v_exp_f32_e32 v40, v40
	v_exp_f32_e32 v41, v41
	v_pk_add_f32 v[38:39], v[38:39], 1.0 op_sel_hi:[1,0]
	v_rcp_f32_e32 v38, v38
	v_rcp_f32_e32 v39, v39
	v_pk_add_f32 v[34:35], v[40:41], 1.0 op_sel_hi:[1,0]
	v_rcp_f32_e32 v34, v34
	v_rcp_f32_e32 v35, v35
	v_mul_f32_e32 v36, v189, v189
	v_pk_mul_f32 v[32:33], v[36:37], v[38:39] op_sel_hi:[0,1]
	v_pk_mul_f32 v[28:29], v[28:29], v[32:33]
	v_pk_mul_f32 v[32:33], v[36:37], v[34:35] op_sel_hi:[0,1]
	v_pk_mul_f32 v[34:35], v[24:25], v[36:37] op_sel:[0,1]
	v_exp_f32_e32 v34, v34
	v_exp_f32_e32 v35, v35
	v_pk_mul_f32 v[30:31], v[30:31], v[32:33]
	v_pk_add_f32 v[32:33], v[34:35], 1.0 op_sel_hi:[1,0]
	v_pk_mul_f32 v[34:35], v[26:27], v[36:37] op_sel:[0,1]
	v_exp_f32_e32 v34, v34
	v_exp_f32_e32 v35, v35
	v_rcp_f32_e32 v32, v32
	v_rcp_f32_e32 v33, v33
	v_pk_add_f32 v[26:27], v[34:35], 1.0 op_sel_hi:[1,0]
	v_rcp_f32_e32 v26, v26
	v_rcp_f32_e32 v27, v27
	v_pk_mul_f32 v[24:25], v[36:37], v[32:33] op_sel_hi:[0,1]
	v_pk_mul_f32 v[24:25], v[20:21], v[24:25]
	v_pk_mul_f32 v[20:21], v[36:37], v[26:27] op_sel_hi:[0,1]
	v_pk_mul_f32 v[26:27], v[22:23], v[20:21]
	v_cvt_pk_bf16_f32 v20, v28, v29
	v_cvt_pk_bf16_f32 v21, v30, v31
	v_cvt_pk_bf16_f32 v22, v24, v25
	v_cvt_pk_bf16_f32 v23, v26, v27
	v_nop
	v_add_u32_e32 v247, 0x1e4000, v246
	global_store_dwordx4 v247, v[20:23], s[2:3]
	s_mov_b64 s[2:3], -1
	s_cbranch_vccnz .LBB0_252
	s_andn2_b64 vcc, exec, s[0:1]
	s_cbranch_vccnz .LBB0_251
	s_barrier
	s_branch .LBB0_251
